# mixer unit prologue de-serialised: Q lands in loop-dead registers, its waits and LDS writes moved behind the first V/K loads (24 loads in flight, one round trip per unit instead of two)
# speedup vs baseline: 1.0002x; 1.0002x over previous
; #define LAS __attribute__((address_space(3)))
; __device__ __forceinline__ void mixer_attn(const bf16_t* Z, bf16_t* MIX, int b, int r, LAS unsigned char* lds) {
;     int tid_l = threadIdx.x; asm volatile("" : "+v"(tid_l));
;     const int tid = tid_l, lane = tid & 63, h = __builtin_amdgcn_readfirstlane(tid >> 6), i = lane & 15, g = lane >> 4;
;     LAS unsigned char* wl = lds + h * WREG;
;     LAS const float* btab = (LAS const float*)(wl + BT_OFF);
;     LAS float* ssbuf = (LAS float*)(lds + SSBUF_OFF);
;     const bf16_t* zq = Z + ((size_t)b * SEQ + r * 64) * NIN + h * 64;
;     LAS unsigned char* qlds = wl + Q_OFF + lane * 16;
; #pragma unroll
;     for (int jq = 0; jq < 4; ++jq)
; #pragma unroll
;         for (int dh = 0; dh < 2; ++dh) *(LAS bf16x8*)(qlds + (2 * jq + dh) * 1024) = *(const bf16x8*)((const char*)zq + (size_t)(((16 * jq) * NIN + 32 * dh) * 2) + (unsigned)(i * NIN + 8 * g) * 2u);
;     f32x4 o[4][4]; float mrun[4], lrun[4]; int m0[4];
; #pragma unroll
;     for (int jq = 0; jq < 4; ++jq) { mrun[jq] = -__builtin_inff(); lrun[jq] = 0.f; m0[jq] = 4 * g - min(max(16 * jq + i - 8, 0), 48);
; #pragma unroll
;         for (int dt = 0; dt < 4; ++dt) o[jq][dt] = (f32x4){0.f, 0.f, 0.f, 0.f}; }
;     const int r0 = min(max(r - 4, 0), 56), c0 = 4 * g - i;
;     LAS unsigned char* vrd = wl + (4 * g + (i >> 2)) * VS + 8 * (i & 3);
;     const bf16_t* kbb = Z + ((size_t)b * SEQ) * NIN + h * 64;
;     const bf16_t* kb0 = kbb + (size_t)((r0 + ((0 - r0) & 7)) * 64) * NIN;
;     const unsigned kfo = (unsigned)(i * NIN + 8 * g) * 2u;
;     const unsigned vfo = (unsigned)((lane >> 3) * NIN + 8 * (lane & 7)) * 2u;
;     ...
;     bf16x8 kf[4][2]; u32x4 vc[8];
; #pragma unroll
;     for (int n = 0; n < 8; ++n) vc[n] = LDV(kb0, n);
;     asm volatile("" ::: "memory");
; #pragma unroll
;     for (int kt = 0; kt < 4; ++kt)
; #pragma unroll
;         for (int dh = 0; dh < 2; ++dh) kf[kt][dh] = LDK(kb0, kt, dh);
;     asm volatile("" ::: "memory");
.LBB0_288:
	s_and_b32 s0, s92, 63
	v_sub_u32_e64 v0, s0, 4 clamp
	v_mov_b32_e32 v44, v232
	v_readfirstlane_b32 s0, v0
	s_min_u32 s0, s0, 56
	s_sub_i32 s85, 0, s0
	s_ashr_i32 s4, s86, 6
	v_readfirstlane_b32 s0, v44
	s_lshr_b32 s1, s0, 6
	s_and_b32 s2, s86, 63
	s_mulk_i32 s1, 0x4d00
	s_ashr_i32 s5, s4, 31
	s_add_i32 s60, s1, 0
	s_lshl_b64 s[88:89], s[4:5], 12
	s_lshl_b32 s1, s2, 6
	s_or_b32 s96, s88, s1
	v_writelane_b32 v255, s1, 34
	s_mul_i32 s1, s89, 0x1800
	s_mul_hi_u32 s5, s96, 0x1800
	s_add_i32 s5, s5, s1
	s_mul_i32 s1, s96, 0x1800
	s_add_u32 s6, s72, s1
	s_addc_u32 s5, s73, s5
	s_andn2_b32 s0, s0, 63
	s_ashr_i32 s1, s0, 31
	v_and_b32_e32 v205, 15, v44
	s_lshl_b64 s[80:81], s[0:1], 1
	s_add_u32 s6, s6, s80
	v_mul_u32_u24_e32 v0, 0x1800, v205
	s_addc_u32 s7, s5, s81
	v_and_or_b32 v156, v44, 48, v0
	v_mov_b32_e32 v157, v193
	v_lshl_add_u64 v[24:25], s[6:7], 0, v[156:157]
	v_add_co_u32_e32 v12, vcc, s3, v24
	global_load_dwordx4 v[132:135], v156, s[6:7]
	global_load_dwordx4 v[136:139], v156, s[6:7] offset:64
	v_addc_co_u32_e32 v13, vcc, 0, v25, vcc
	v_add_co_u32_e32 v20, vcc, s78, v24
	global_load_dwordx4 v[140:143], v[12:13], off
	s_nop 0
	global_load_dwordx4 v[144:147], v[12:13], off offset:64
	v_addc_co_u32_e32 v21, vcc, 0, v25, vcc
	v_add_co_u32_e32 v28, vcc, s79, v24
	global_load_dwordx4 v[148:151], v[20:21], off
	s_nop 0
	global_load_dwordx4 v[62:65], v[20:21], off offset:64
	v_addc_co_u32_e32 v29, vcc, 0, v25, vcc
	global_load_dwordx4 v[66:69], v[28:29], off
	s_nop 0
	global_load_dwordx4 v[70:73], v[28:29], off offset:64
	v_sub_u32_e64 v32, s2, 4 clamp
	s_mul_hi_i32 s5, s4, 0x1800000
	v_readfirstlane_b32 s1, v32
	s_mul_i32 s4, s4, 0x1800000
	s_min_u32 s1, s1, 56
	s_add_u32 s4, s72, s4
	s_addc_u32 s5, s73, s5
	s_add_u32 s82, s4, s80
	s_addc_u32 s93, s5, s81
	s_sub_i32 s4, 0, s1
	v_and_b32_e32 v209, 63, v44
	s_and_b32 s4, s4, 7
	v_bfe_u32 v45, v44, 3, 3
	v_lshlrev_b32_e32 v35, 4, v209
	s_add_i32 s4, s4, s1
	v_lshlrev_b32_e32 v34, 3, v44
	v_mul_u32_u24_e32 v37, 0xc00, v45
	v_add_u32_e32 v210, s60, v35
	s_mul_i32 s4, s4, 0x60000
	s_add_u32 s4, s82, s4
	s_addc_u32 s5, s93, 0
	v_mov_b32_e32 v161, v193
	s_mov_b32 s77, 0xc000
	s_mov_b32 s94, 0x24000
	s_mov_b32 s95, 0x3c000
	v_bfe_u32 v32, v44, 2, 4
	s_movk_i32 s6, 0x90
	v_lshrrev_b32_e32 v33, 2, v44
	v_and_b32_e32 v208, 12, v33
	v_sub_u32_e64 v33, v205, 8 clamp
	v_min_u32_e32 v36, 8, v205
	v_and_b32_e32 v46, 24, v34
	v_sub_u32_e32 v47, v208, v33
	v_sub_u32_e32 v49, v208, v36
	v_sub_u32_e32 v48, v208, v205
	v_add_u32_e32 v50, -8, v48
	s_movk_i32 s50, 0xffe0
	v_subrev_u32_e32 v51, 24, v48
	v_subrev_u32_e32 v60, 40, v49
	s_movk_i32 s58, 0xffd0
	s_movk_i32 s44, 0xffef
	v_lshl_add_u32 v211, v48, 2, s60
	v_add_u32_e32 v128, 10, v49
	v_add_u32_e32 v129, 11, v49
	s_mov_b32 s33, 0
	s_mov_b32 s97, s89
	s_sub_i32 s2, s1, s2
	v_cmp_lt_u32_e64 s[10:11], s44, v47
	v_cmp_gt_u32_e64 s[18:19], 16, v50
	v_cmp_lt_u32_e64 s[26:27], s44, v50
	v_cmp_lt_u32_e64 s[44:45], s44, v51
	v_mov_b32_e32 v192, 0xff800000
	v_mov_b32_e32 v216, 0xff800000
	v_mov_b32_e32 v215, 0xff800000
	v_and_or_b32 v0, v34, 56, v37
	v_lshlrev_b32_e32 v160, 1, v0
	v_lshl_add_u64 v[0:1], s[4:5], 0, v[160:161]
	v_add_co_u32_e32 v2, vcc, s77, v0
	v_mov_b32_e32 v16, 0
	s_nop 0
	v_addc_co_u32_e32 v3, vcc, 0, v1, vcc
	v_add_co_u32_e32 v4, vcc, s3, v0
	v_mov_b32_e32 v214, 0xff800000
	s_nop 0
	v_addc_co_u32_e32 v5, vcc, 0, v1, vcc
	global_load_dwordx4 v[96:99], v[2:3], off offset:2048
	global_load_dwordx4 v[100:103], v[4:5], off offset:2048
	v_add_co_u32_e32 v2, vcc, s94, v0
	v_mov_b32_e32 v17, v16
	s_nop 0
	v_addc_co_u32_e32 v3, vcc, 0, v1, vcc
	v_add_co_u32_e32 v4, vcc, s78, v0
	v_mov_b32_e32 v18, v16
	s_nop 0
	v_addc_co_u32_e32 v5, vcc, 0, v1, vcc
	global_load_dwordx4 v[108:111], v[2:3], off offset:2048
	global_load_dwordx4 v[112:115], v[4:5], off offset:2048
	v_add_co_u32_e32 v2, vcc, s95, v0
	v_mov_b32_e32 v19, v16
	s_nop 0
	v_addc_co_u32_e32 v3, vcc, 0, v1, vcc
	v_add_co_u32_e32 v4, vcc, s79, v0
	v_mov_b32_e32 v24, v16
	s_nop 0
	v_addc_co_u32_e32 v5, vcc, 0, v1, vcc
	v_add_co_u32_e32 v0, vcc, s99, v0
	global_load_dwordx4 v[116:119], v[2:3], off offset:2048
	global_load_dwordx4 v[120:123], v[4:5], off offset:2048
	v_addc_co_u32_e32 v1, vcc, 0, v1, vcc
	global_load_dwordx4 v[104:107], v160, s[4:5] offset:2048
	global_load_dwordx4 v[124:127], v[0:1], off offset:2048
	v_mov_b32_e32 v0, s60
	v_mad_u32_u24 v4, v32, s6, v0
	v_lshl_add_u64 v[0:1], s[4:5], 0, v[156:157]
	v_add_co_u32_e32 v2, vcc, s3, v0
	global_load_dwordx4 v[40:43], v156, s[4:5] offset:1024
	global_load_dwordx4 v[36:39], v156, s[4:5] offset:1088
	v_addc_co_u32_e32 v3, vcc, 0, v1, vcc
	global_load_dwordx4 v[32:35], v[2:3], off offset:1024
	global_load_dwordx4 v[92:95], v[2:3], off offset:1088
	v_add_co_u32_e32 v2, vcc, s78, v0
	v_add_u32_e32 v213, v4, v46
	s_nop 0
	v_addc_co_u32_e32 v3, vcc, 0, v1, vcc
	v_add_co_u32_e32 v0, vcc, s79, v0
	global_load_dwordx4 v[20:23], v[2:3], off offset:1024
	global_load_dwordx4 v[56:59], v[2:3], off offset:1088
	v_addc_co_u32_e32 v1, vcc, 0, v1, vcc
	global_load_dwordx4 v[80:83], v[0:1], off offset:1024
	global_load_dwordx4 v[52:55], v[0:1], off offset:1088
	s_waitcnt vmcnt(23)
; #define LAS __attribute__((address_space(3)))
; __device__ __forceinline__ void mixer_attn(const bf16_t* Z, bf16_t* MIX, int b, int r, LAS unsigned char* lds) {
;     ...
;         for (int dh = 0; dh < 2; ++dh) *(LAS bf16x8*)(qlds + (2 * jq + dh) * 1024) = *(const bf16x8*)((const char*)zq + (size_t)(((16 * jq) * NIN + 32 * dh) * 2) + (unsigned)(i * NIN + 8 * g) * 2u);
;     f32x4 o[4][4]; float mrun[4], lrun[4]; int m0[4];
; #pragma unroll
;     for (int jq = 0; jq < 4; ++jq) { mrun[jq] = -__builtin_inff(); lrun[jq] = 0.f; m0[jq] = 4 * g - min(max(16 * jq + i - 8, 0), 48);
; #pragma unroll
;         for (int dt = 0; dt < 4; ++dt) o[jq][dt] = (f32x4){0.f, 0.f, 0.f, 0.f}; }
;     const int r0 = min(max(r - 4, 0), 56), c0 = 4 * g - i;
	ds_write_b128 v210, v[132:135] offset:11520
	s_waitcnt vmcnt(22)
	ds_write_b128 v210, v[136:139] offset:12544
	s_waitcnt vmcnt(21)
	ds_write_b128 v210, v[140:143] offset:13568
	s_waitcnt vmcnt(20)
	ds_write_b128 v210, v[144:147] offset:14592
	s_waitcnt vmcnt(19)
	ds_write_b128 v210, v[148:151] offset:15616
	s_waitcnt vmcnt(18)
	ds_write_b128 v210, v[62:65] offset:16640
	s_waitcnt vmcnt(17)
	ds_write_b128 v210, v[66:69] offset:17664
	s_waitcnt vmcnt(16)
	ds_write_b128 v210, v[70:73] offset:18688
	v_add_u32_e32 v1, 1, v47
	v_cmp_gt_u32_e64 s[4:5], 16, v1
	v_add_u32_e32 v1, 2, v47
	v_cmp_gt_u32_e64 s[6:7], 16, v1
	v_add_u32_e32 v1, 3, v47
	v_cmp_gt_u32_e64 s[8:9], 16, v1
	v_add_u32_e32 v1, 17, v47
	v_cmp_gt_u32_e64 s[12:13], 16, v1
	v_add_u32_e32 v1, 18, v47
	v_cmp_gt_u32_e64 s[14:15], 16, v1
	v_add_u32_e32 v1, 19, v47
	v_cmp_gt_u32_e64 s[16:17], 16, v1
	v_add_u32_e32 v1, -7, v48
	v_cmp_gt_u32_e64 s[20:21], 16, v1
	v_add_u32_e32 v1, -6, v48
	v_cmp_gt_u32_e64 s[22:23], 16, v1
	v_add_u32_e32 v1, -5, v48
	v_cmp_gt_u32_e64 s[24:25], 16, v1
	v_add_u32_e32 v1, 9, v48
	v_cmp_gt_u32_e64 s[28:29], 16, v1
	v_add_u32_e32 v1, 10, v48
	v_cmp_gt_u32_e64 s[30:31], 16, v1
	v_add_u32_e32 v1, 11, v48
	v_cmp_gt_u32_e64 s[34:35], 16, v1
	v_and_b32_e32 v1, -16, v50
	v_cmp_eq_u32_e64 s[36:37], s50, v1
	v_add_u32_e32 v1, 25, v48
	v_cmp_gt_u32_e64 s[38:39], 16, v1
	v_add_u32_e32 v1, 26, v48
	v_cmp_gt_u32_e64 s[40:41], 16, v1
	v_add_u32_e32 v1, 27, v48
	v_cmp_gt_u32_e64 s[42:43], 16, v1
	v_and_b32_e32 v1, -16, v51
	v_lshlrev_b32_e32 v0, 4, v44
	v_cmp_eq_u32_e64 s[46:47], s50, v1
	v_cmp_eq_u32_e64 s[48:49], s58, v1
	v_and_b32_e32 v1, -16, v60
	v_add_u32_e32 v2, -7, v49
	v_and_b32_e32 v0, 0x70, v0
	v_cmp_eq_u32_e64 s[50:51], s50, v1
	v_cmp_gt_u32_e64 s[52:53], 16, v2
	v_add_u32_e32 v2, -6, v49
	v_cmp_eq_u32_e64 s[58:59], s58, v1
	v_add_u32_e32 v1, 9, v49
	v_add_u32_e32 v0, s60, v0
	v_cmp_gt_u32_e64 s[54:55], 16, v2
	v_add_u32_e32 v2, -5, v49
	v_cmp_gt_u32_e64 s[60:61], 16, v1
	v_mul_u32_u24_e32 v1, 0x90, v45
	v_cmp_gt_u32_e32 vcc, 16, v47
	v_cmp_gt_u32_e64 s[56:57], 16, v2
	v_add_u32_e32 v212, v0, v1
	v_mov_b32_e32 v25, v16
	v_mov_b32_e32 v26, v16
	v_mov_b32_e32 v27, v16
	v_mov_b32_e32 v28, v16
	v_mov_b32_e32 v29, v16
	v_mov_b32_e32 v30, v16
	v_mov_b32_e32 v31, v16
	v_mov_b32_e32 v44, v16
	v_mov_b32_e32 v45, v16
	v_mov_b32_e32 v46, v16
	v_mov_b32_e32 v47, v16
	v_mov_b32_e32 v60, v16
	v_mov_b32_e32 v61, v16
	v_mov_b32_e32 v62, v16
	v_mov_b32_e32 v63, v16
	v_mov_b32_e32 v64, v16
	v_mov_b32_e32 v65, v16
	v_mov_b32_e32 v66, v16
	v_mov_b32_e32 v67, v16
	v_mov_b32_e32 v72, v16
	v_mov_b32_e32 v73, v16
	v_mov_b32_e32 v74, v16
	v_mov_b32_e32 v75, v16
	v_mov_b32_e32 v84, v16
	v_mov_b32_e32 v85, v16
	v_mov_b32_e32 v86, v16
	v_mov_b32_e32 v87, v16
	v_mov_b32_e32 v88, v16
	v_mov_b32_e32 v89, v16
	v_mov_b32_e32 v90, v16
	v_mov_b32_e32 v91, v16
	v_mov_b32_e32 v76, v16
	v_mov_b32_e32 v77, v16
	v_mov_b32_e32 v78, v16
	v_mov_b32_e32 v79, v16
	v_mov_b32_e32 v68, v16
	v_mov_b32_e32 v69, v16
	v_mov_b32_e32 v70, v16
	v_mov_b32_e32 v71, v16
	v_mov_b32_e32 v48, v16
	v_mov_b32_e32 v49, v16
	v_mov_b32_e32 v50, v16
	v_mov_b32_e32 v51, v16
	v_mov_b32_e32 v12, v16
	v_mov_b32_e32 v13, v16
	v_mov_b32_e32 v14, v16
	v_mov_b32_e32 v15, v16
	v_mov_b32_e32 v8, v16
	v_mov_b32_e32 v9, v16
	v_mov_b32_e32 v10, v16
	v_mov_b32_e32 v11, v16
	v_mov_b32_e32 v4, v16
	v_mov_b32_e32 v5, v16
	v_mov_b32_e32 v6, v16
	v_mov_b32_e32 v7, v16
	v_mov_b32_e32 v0, v16
	v_mov_b32_e32 v1, v16
	v_mov_b32_e32 v2, v16
	v_mov_b32_e32 v3, v16
	v_mov_b32_e32 v158, v16
	v_mov_b32_e32 v159, v16
	v_mov_b32_e32 v162, v16
	v_mov_b32_e32 v163, v16
	v_cmp_gt_u32_e64 s[62:63], 16, v128
	v_cmp_gt_u32_e64 s[64:65], 16, v129
